# v30
# speedup vs baseline: 1.0015x; 1.0015x over previous
.LBB0_179:
	s_or_b64 exec, exec, s[78:79]
	v_max_f32_e32 v1, v76, v77
	v_max_f32_e32 v112, v92, v93
	v_max3_f32 v1, v74, v75, v1
	v_max3_f32 v112, v90, v91, v112
	v_max3_f32 v1, v1, s41, v112
	v_max_f32_e32 v112, v80, v81
	v_max_f32_e32 v113, v96, v97
	v_max3_f32 v112, v78, v79, v112
	v_max3_f32 v113, v94, v95, v113
	v_max3_f32 v1, v1, v112, v113
	ds_bpermute_b32 v112, v135, v1
	s_waitcnt lgkmcnt(0)
	v_max_f32_e32 v1, v1, v112
	ds_bpermute_b32 v112, v101, v1
	s_waitcnt lgkmcnt(0)
	v_max3_f32 v1, v111, v1, v112
	v_sub_f32_e32 v74, v74, v1
	v_sub_f32_e32 v112, v111, v1
	v_exp_f32_e32 v111, v74
	v_sub_f32_e32 v74, v75, v1
	v_exp_f32_e32 v113, v74
	v_sub_f32_e32 v74, v76, v1
	v_exp_f32_e32 v115, v74
	v_sub_f32_e32 v74, v77, v1
	v_exp_f32_e32 v117, v74
	v_sub_f32_e32 v74, v90, v1
	v_exp_f32_e32 v119, v74
	v_sub_f32_e32 v74, v91, v1
	v_exp_f32_e32 v91, v74
	v_sub_f32_e32 v74, v92, v1
	v_exp_f32_e32 v121, v74
	v_sub_f32_e32 v74, v93, v1
	v_exp_f32_e32 v93, v74
	v_sub_f32_e32 v74, v78, v1
	v_exp_f32_e32 v123, v74
	v_sub_f32_e32 v74, v79, v1
	v_exp_f32_e32 v125, v74
	v_sub_f32_e32 v74, v80, v1
	v_exp_f32_e32 v127, v74
	v_sub_f32_e32 v74, v81, v1
	v_exp_f32_e32 v129, v74
	v_sub_f32_e32 v74, v94, v1
	v_max_f32_e32 v90, v84, v85
	v_max_f32_e32 v92, v88, v89
	v_max3_f32 v90, v82, v83, v90
	v_max3_f32 v92, v86, v87, v92
	v_exp_f32_e32 v131, v74
	v_sub_f32_e32 v74, v95, v1
	v_max3_f32 v90, v90, s41, v92
	v_exp_f32_e32 v95, v74
	v_sub_f32_e32 v74, v96, v1
	v_max_f32_e32 v92, v68, v69
	v_max_f32_e32 v94, v72, v73
	v_max3_f32 v92, v66, v67, v92
	v_max3_f32 v94, v70, v71, v94
	v_max3_f32 v90, v90, v92, v94
	ds_bpermute_b32 v92, v135, v90
	v_exp_f32_e32 v134, v112
	v_exp_f32_e32 v133, v74
	v_sub_f32_e32 v74, v97, v1
	v_exp_f32_e32 v97, v74
	s_waitcnt lgkmcnt(0)
	v_max_f32_e32 v90, v90, v92
	ds_bpermute_b32 v92, v101, v90
	v_pk_mul_f32 v[80:81], v[52:53], v[134:135] op_sel_hi:[1,0]
	v_pk_mul_f32 v[78:79], v[50:51], v[134:135] op_sel_hi:[1,0]
	v_pk_mul_f32 v[76:77], v[56:57], v[134:135] op_sel_hi:[1,0]
	v_pk_mul_f32 v[74:75], v[54:55], v[134:135] op_sel_hi:[1,0]
	s_waitcnt lgkmcnt(0)
	v_max3_f32 v151, v110, v90, v92
	v_sub_f32_e32 v82, v82, v151
	v_sub_f32_e32 v152, v110, v151
	v_exp_f32_e32 v110, v82
	v_sub_f32_e32 v82, v83, v151
	v_exp_f32_e32 v112, v82
	v_sub_f32_e32 v82, v84, v151
	v_exp_f32_e32 v114, v82
	v_sub_f32_e32 v82, v85, v151
	v_sub_f32_e32 v66, v66, v151
	v_exp_f32_e32 v116, v82
	v_sub_f32_e32 v82, v86, v151
	v_exp_f32_e32 v122, v66
	v_sub_f32_e32 v66, v67, v151
	v_exp_f32_e32 v118, v82
	v_sub_f32_e32 v82, v87, v151
	v_exp_f32_e32 v124, v66
	v_exp_f32_e32 v90, v82
	v_sub_f32_e32 v82, v88, v151
	v_pk_add_f32 v[66:67], v[112:113], v[110:111]
	v_exp_f32_e32 v120, v82
	v_sub_f32_e32 v82, v89, v151
	v_pk_add_f32 v[66:67], v[114:115], v[66:67]
	v_exp_f32_e32 v92, v82
	v_pk_add_f32 v[66:67], v[116:117], v[66:67]
	v_sub_f32_e32 v68, v68, v151
	v_pk_add_f32 v[66:67], v[118:119], v[66:67]
	v_exp_f32_e32 v126, v68
	v_pk_add_f32 v[66:67], v[90:91], v[66:67]
	v_sub_f32_e32 v68, v69, v151
	v_pk_add_f32 v[66:67], v[120:121], v[66:67]
	v_exp_f32_e32 v128, v68
	v_pk_add_f32 v[66:67], v[92:93], v[66:67]
	v_sub_f32_e32 v68, v70, v151
	v_pk_add_f32 v[66:67], v[122:123], v[66:67]
	v_exp_f32_e32 v130, v68
	v_sub_f32_e32 v68, v71, v151
	v_pk_add_f32 v[66:67], v[124:125], v[66:67]
	v_exp_f32_e32 v94, v68
	v_sub_f32_e32 v68, v72, v151
	v_exp_f32_e32 v132, v68
	v_sub_f32_e32 v68, v73, v151
	v_pk_add_f32 v[66:67], v[126:127], v[66:67]
	v_exp_f32_e32 v96, v68
	v_pk_add_f32 v[66:67], v[128:129], v[66:67]
	v_exp_f32_e32 v82, v152
	v_pk_add_f32 v[66:67], v[130:131], v[66:67]
	v_mov_b32_e32 v83, v134
	v_pk_add_f32 v[66:67], v[94:95], v[66:67]
	v_pk_add_f32 v[66:67], v[132:133], v[66:67]
	v_pk_mul_f32 v[68:69], v[36:37], v[82:83] op_sel_hi:[1,0]
	v_pk_add_f32 v[66:67], v[96:97], v[66:67]
	v_pk_mul_f32 v[72:73], v[40:41], v[82:83] op_sel_hi:[1,0]
	v_pk_fma_f32 v[104:105], v[104:105], v[82:83], v[66:67]
	v_pk_mul_f32 v[66:67], v[34:35], v[82:83] op_sel_hi:[1,0]
	v_pk_mul_f32 v[70:71], v[38:39], v[82:83] op_sel_hi:[1,0]
	v_pk_mul_f32 v[44:45], v[44:45], v[82:83] op_sel_hi:[1,0]
	v_pk_mul_f32 v[42:43], v[42:43], v[82:83] op_sel_hi:[1,0]
	v_pk_mul_f32 v[36:37], v[48:49], v[82:83] op_sel_hi:[1,0]
	v_pk_mul_f32 v[34:35], v[46:47], v[82:83] op_sel_hi:[1,0]
	ds_read_b128 v[154:157], v188 offset:25088
	ds_read_b128 v[158:161], v188 offset:27136
	ds_read_b128 v[162:165], v188 offset:29184
	ds_read_b128 v[166:169], v188 offset:31232
	ds_read_b128 v[170:173], v189 offset:27136
	ds_read_b128 v[174:177], v189 offset:25088
	ds_read_b128 v[178:181], v189 offset:29184
	ds_read_b128 v[182:185], v189 offset:31232
	v_cvt_pk_bf16_f32 v54, v111, v113
	v_cvt_pk_bf16_f32 v55, v115, v117
	v_cvt_pk_bf16_f32 v56, v119, v91
	v_cvt_pk_bf16_f32 v57, v121, v93
	v_cvt_pk_bf16_f32 v38, v110, v112
	v_cvt_pk_bf16_f32 v39, v114, v116
	v_cvt_pk_bf16_f32 v40, v118, v90
	v_cvt_pk_bf16_f32 v41, v120, v92
	v_pk_mul_f32 v[60:61], v[60:61], v[134:135] op_sel_hi:[1,0]
	s_waitcnt lgkmcnt(7)
	v_mfma_f32_16x16x32_bf16 v[78:81], v[154:157], v[54:57], v[78:81]
	v_mul_f32_e64 v58, v58, v134
	v_mul_f32_e64 v59, v59, v134
	v_pk_mul_f32 v[52:53], v[64:65], v[134:135] op_sel_hi:[1,0]
	v_pk_mul_f32 v[50:51], v[62:63], v[134:135] op_sel_hi:[1,0]
	v_mfma_f32_16x16x32_bf16 v[66:69], v[154:157], v[38:41], v[66:69]
	v_cvt_pk_bf16_f32 v62, v123, v125
	s_waitcnt lgkmcnt(6)
	v_mfma_f32_16x16x32_bf16 v[74:77], v[158:161], v[54:57], v[74:77]
	v_cvt_pk_bf16_f32 v63, v127, v129
	v_cvt_pk_bf16_f32 v64, v131, v95
	v_cvt_pk_bf16_f32 v65, v133, v97
	v_mfma_f32_16x16x32_bf16 v[70:73], v[158:161], v[38:41], v[70:73]
	v_cvt_pk_bf16_f32 v46, v122, v124
	v_cvt_pk_bf16_f32 v47, v126, v128
	s_waitcnt lgkmcnt(5)
	v_mfma_f32_16x16x32_bf16 v[58:61], v[162:165], v[54:57], v[58:61]
	v_cvt_pk_bf16_f32 v48, v130, v94
	v_cvt_pk_bf16_f32 v49, v132, v96
	v_mov_b32_e32 v110, v151
	v_mfma_f32_16x16x32_bf16 v[42:45], v[162:165], v[38:41], v[42:45]
	v_mov_b32_e32 v111, v1
	s_waitcnt lgkmcnt(4)
	v_mfma_f32_16x16x32_bf16 v[86:89], v[166:169], v[54:57], v[50:53]
	v_mfma_f32_16x16x32_bf16 v[82:85], v[166:169], v[38:41], v[34:37]
	s_waitcnt lgkmcnt(2)
	v_mfma_f32_16x16x32_bf16 v[50:53], v[174:177], v[62:65], v[78:81]
	v_mfma_f32_16x16x32_bf16 v[34:37], v[174:177], v[46:49], v[66:69]
	s_waitcnt lgkmcnt(1)
	v_mfma_f32_16x16x32_bf16 v[58:61], v[178:181], v[62:65], v[58:61]
	v_mfma_f32_16x16x32_bf16 v[42:45], v[178:181], v[46:49], v[42:45]
	v_mfma_f32_16x16x32_bf16 v[54:57], v[170:173], v[62:65], v[74:77]
	v_mfma_f32_16x16x32_bf16 v[38:41], v[170:173], v[46:49], v[70:73]
	s_waitcnt lgkmcnt(0)
	v_mfma_f32_16x16x32_bf16 v[62:65], v[182:185], v[62:65], v[86:89]
	v_mfma_f32_16x16x32_bf16 v[46:49], v[182:185], v[46:49], v[82:85]

.LBB0_188:
	s_or_b64 exec, exec, s[78:79]
	v_max_f32_e32 v1, v68, v69
	v_max_f32_e32 v112, v92, v93
	v_max3_f32 v1, v66, v67, v1
	v_max3_f32 v112, v90, v91, v112
	v_max3_f32 v1, v1, s41, v112
	v_max_f32_e32 v112, v84, v85
	v_max_f32_e32 v113, v96, v97
	v_max3_f32 v112, v82, v83, v112
	v_max3_f32 v113, v94, v95, v113
	v_max3_f32 v1, v1, v112, v113
	ds_bpermute_b32 v112, v135, v1
	s_waitcnt lgkmcnt(0)
	v_max_f32_e32 v1, v1, v112
	ds_bpermute_b32 v112, v101, v1
	s_waitcnt lgkmcnt(0)
	v_max3_f32 v1, v111, v1, v112
	v_sub_f32_e32 v66, v66, v1
	v_sub_f32_e32 v112, v111, v1
	v_exp_f32_e32 v111, v66
	v_sub_f32_e32 v66, v67, v1
	v_exp_f32_e32 v113, v66
	v_sub_f32_e32 v66, v68, v1
	v_exp_f32_e32 v115, v66
	v_sub_f32_e32 v66, v69, v1
	v_exp_f32_e32 v117, v66
	v_sub_f32_e32 v66, v90, v1
	v_exp_f32_e32 v119, v66
	v_sub_f32_e32 v66, v91, v1
	v_exp_f32_e32 v91, v66
	v_sub_f32_e32 v66, v92, v1
	v_exp_f32_e32 v121, v66
	v_sub_f32_e32 v66, v93, v1
	v_exp_f32_e32 v93, v66
	v_sub_f32_e32 v66, v82, v1
	v_exp_f32_e32 v123, v66
	v_sub_f32_e32 v66, v83, v1
	v_exp_f32_e32 v125, v66
	v_sub_f32_e32 v66, v84, v1
	v_exp_f32_e32 v127, v66
	v_sub_f32_e32 v66, v85, v1
	v_exp_f32_e32 v129, v66
	v_sub_f32_e32 v66, v94, v1
	v_max_f32_e32 v90, v88, v89
	v_max_f32_e32 v92, v76, v77
	v_max3_f32 v90, v86, v87, v90
	v_max3_f32 v92, v74, v75, v92
	v_exp_f32_e32 v131, v66
	v_sub_f32_e32 v66, v95, v1
	v_max3_f32 v90, v90, s41, v92
	v_exp_f32_e32 v95, v66
	v_sub_f32_e32 v66, v96, v1
	v_max_f32_e32 v92, v72, v73
	v_max_f32_e32 v94, v80, v81
	v_max3_f32 v92, v70, v71, v92
	v_max3_f32 v94, v78, v79, v94
	v_max3_f32 v90, v90, v92, v94
	ds_bpermute_b32 v92, v135, v90
	v_exp_f32_e32 v152, v112
	v_exp_f32_e32 v133, v66
	v_sub_f32_e32 v66, v97, v1
	v_exp_f32_e32 v97, v66
	s_waitcnt lgkmcnt(0)
	v_max_f32_e32 v90, v90, v92
	ds_bpermute_b32 v92, v101, v90
	v_pk_mul_f32 v[84:85], v[52:53], v[152:153] op_sel_hi:[1,0]
	v_pk_mul_f32 v[82:83], v[50:51], v[152:153] op_sel_hi:[1,0]
	v_pk_mul_f32 v[68:69], v[56:57], v[152:153] op_sel_hi:[1,0]
	v_pk_mul_f32 v[66:67], v[54:55], v[152:153] op_sel_hi:[1,0]
	s_waitcnt lgkmcnt(0)
	v_max3_f32 v134, v110, v90, v92
	v_sub_f32_e32 v86, v86, v134
	v_sub_f32_e32 v151, v110, v134
	v_exp_f32_e32 v110, v86
	v_sub_f32_e32 v86, v87, v134
	v_exp_f32_e32 v112, v86
	v_sub_f32_e32 v86, v88, v134
	v_sub_f32_e32 v74, v74, v134
	v_exp_f32_e32 v114, v86
	v_sub_f32_e32 v86, v89, v134
	v_exp_f32_e32 v118, v74
	v_sub_f32_e32 v74, v75, v134
	v_exp_f32_e32 v116, v86
	v_exp_f32_e32 v90, v74
	v_sub_f32_e32 v74, v76, v134
	v_sub_f32_e32 v70, v70, v134
	v_exp_f32_e32 v120, v74
	v_exp_f32_e32 v122, v70
	v_sub_f32_e32 v70, v71, v134
	v_pk_add_f32 v[74:75], v[112:113], v[110:111]
	v_exp_f32_e32 v124, v70
	v_sub_f32_e32 v70, v72, v134
	v_pk_add_f32 v[74:75], v[114:115], v[74:75]
	v_sub_f32_e32 v76, v77, v134
	v_exp_f32_e32 v126, v70
	v_sub_f32_e32 v70, v73, v134
	v_pk_add_f32 v[74:75], v[116:117], v[74:75]
	v_exp_f32_e32 v92, v76
	v_exp_f32_e32 v128, v70
	v_sub_f32_e32 v70, v78, v134
	v_pk_add_f32 v[74:75], v[118:119], v[74:75]
	v_exp_f32_e32 v130, v70
	v_sub_f32_e32 v70, v79, v134
	v_pk_add_f32 v[74:75], v[90:91], v[74:75]
	v_exp_f32_e32 v94, v70
	v_sub_f32_e32 v70, v80, v134
	v_pk_add_f32 v[74:75], v[120:121], v[74:75]
	v_exp_f32_e32 v132, v70
	v_sub_f32_e32 v70, v81, v134
	v_exp_f32_e32 v96, v70
	v_pk_add_f32 v[70:71], v[92:93], v[74:75]
	v_exp_f32_e32 v78, v151
	v_pk_add_f32 v[70:71], v[122:123], v[70:71]
	v_mov_b32_e32 v79, v152
	v_pk_add_f32 v[70:71], v[124:125], v[70:71]
	v_pk_add_f32 v[70:71], v[126:127], v[70:71]
	v_pk_mul_f32 v[76:77], v[36:37], v[78:79] op_sel_hi:[1,0]
	v_pk_add_f32 v[70:71], v[128:129], v[70:71]
	v_pk_mul_f32 v[74:75], v[34:35], v[78:79] op_sel_hi:[1,0]
	v_pk_add_f32 v[70:71], v[130:131], v[70:71]
	v_pk_mul_f32 v[72:73], v[40:41], v[78:79] op_sel_hi:[1,0]
	v_pk_add_f32 v[70:71], v[94:95], v[70:71]
	v_pk_mul_f32 v[44:45], v[44:45], v[78:79] op_sel_hi:[1,0]
	v_pk_add_f32 v[70:71], v[132:133], v[70:71]
	v_pk_mul_f32 v[42:43], v[42:43], v[78:79] op_sel_hi:[1,0]
	v_pk_add_f32 v[70:71], v[96:97], v[70:71]
	v_pk_mul_f32 v[36:37], v[48:49], v[78:79] op_sel_hi:[1,0]
	v_pk_fma_f32 v[104:105], v[104:105], v[78:79], v[70:71]
	v_pk_mul_f32 v[70:71], v[38:39], v[78:79] op_sel_hi:[1,0]
	v_pk_mul_f32 v[34:35], v[46:47], v[78:79] op_sel_hi:[1,0]
	ds_read_b128 v[154:157], v188 offset:33280
	ds_read_b128 v[158:161], v188 offset:35328
	ds_read_b128 v[162:165], v188 offset:37376
	ds_read_b128 v[166:169], v188 offset:39424
	ds_read_b128 v[170:173], v189 offset:35328
	ds_read_b128 v[174:177], v189 offset:33280
	ds_read_b128 v[178:181], v189 offset:37376
	ds_read_b128 v[182:185], v189 offset:39424
	v_cvt_pk_bf16_f32 v54, v111, v113
	v_cvt_pk_bf16_f32 v55, v115, v117
	v_cvt_pk_bf16_f32 v56, v119, v91
	v_cvt_pk_bf16_f32 v57, v121, v93
	v_cvt_pk_bf16_f32 v38, v110, v112
	v_cvt_pk_bf16_f32 v39, v114, v116
	v_cvt_pk_bf16_f32 v40, v118, v90
	v_cvt_pk_bf16_f32 v41, v120, v92
	v_pk_mul_f32 v[60:61], v[60:61], v[152:153] op_sel_hi:[1,0]
	s_waitcnt lgkmcnt(7)
	v_mfma_f32_16x16x32_bf16 v[82:85], v[154:157], v[54:57], v[82:85]
	v_mul_f32_e64 v58, v58, v152
	v_mul_f32_e64 v59, v59, v152
	v_pk_mul_f32 v[52:53], v[64:65], v[152:153] op_sel_hi:[1,0]
	v_pk_mul_f32 v[50:51], v[62:63], v[152:153] op_sel_hi:[1,0]
	v_mfma_f32_16x16x32_bf16 v[74:77], v[154:157], v[38:41], v[74:77]
	v_cvt_pk_bf16_f32 v62, v123, v125
	s_waitcnt lgkmcnt(6)
	v_mfma_f32_16x16x32_bf16 v[66:69], v[158:161], v[54:57], v[66:69]
	v_cvt_pk_bf16_f32 v63, v127, v129
	v_cvt_pk_bf16_f32 v64, v131, v95
	v_cvt_pk_bf16_f32 v65, v133, v97
	v_mfma_f32_16x16x32_bf16 v[70:73], v[158:161], v[38:41], v[70:73]
	v_cvt_pk_bf16_f32 v46, v122, v124
	v_cvt_pk_bf16_f32 v47, v126, v128
	s_waitcnt lgkmcnt(5)
	v_mfma_f32_16x16x32_bf16 v[58:61], v[162:165], v[54:57], v[58:61]
	v_cvt_pk_bf16_f32 v48, v130, v94
	v_cvt_pk_bf16_f32 v49, v132, v96
	v_mov_b32_e32 v110, v134
	v_mfma_f32_16x16x32_bf16 v[42:45], v[162:165], v[38:41], v[42:45]
	v_mov_b32_e32 v111, v1
	s_waitcnt lgkmcnt(4)
	v_mfma_f32_16x16x32_bf16 v[86:89], v[166:169], v[54:57], v[50:53]
	v_mfma_f32_16x16x32_bf16 v[78:81], v[166:169], v[38:41], v[34:37]
	s_waitcnt lgkmcnt(3)
	v_mfma_f32_16x16x32_bf16 v[54:57], v[170:173], v[62:65], v[66:69]
	s_waitcnt lgkmcnt(1)
	v_mfma_f32_16x16x32_bf16 v[58:61], v[178:181], v[62:65], v[58:61]
	v_mfma_f32_16x16x32_bf16 v[42:45], v[178:181], v[46:49], v[42:45]
	v_mfma_f32_16x16x32_bf16 v[50:53], v[174:177], v[62:65], v[82:85]
	v_mfma_f32_16x16x32_bf16 v[34:37], v[174:177], v[46:49], v[74:77]
	v_mfma_f32_16x16x32_bf16 v[38:41], v[170:173], v[46:49], v[70:73]
	s_waitcnt lgkmcnt(0)
	v_mfma_f32_16x16x32_bf16 v[62:65], v[182:185], v[62:65], v[86:89]
	v_mfma_f32_16x16x32_bf16 v[46:49], v[182:185], v[46:49], v[78:81]

.LBB0_211:
	s_or_b64 exec, exec, s[82:83]
	v_max_f32_e32 v1, v76, v77
	v_max_f32_e32 v112, v92, v93
	v_max3_f32 v1, v74, v75, v1
	v_max3_f32 v112, v90, v91, v112
	v_max3_f32 v1, v1, s41, v112
	v_max_f32_e32 v112, v80, v81
	v_max_f32_e32 v113, v96, v97
	v_max3_f32 v112, v78, v79, v112
	v_max3_f32 v113, v94, v95, v113
	v_max3_f32 v1, v1, v112, v113
	ds_bpermute_b32 v112, v135, v1
	s_waitcnt lgkmcnt(0)
	v_max_f32_e32 v1, v1, v112
	ds_bpermute_b32 v112, v101, v1
	s_waitcnt lgkmcnt(0)
	v_max3_f32 v1, v111, v1, v112
	v_sub_f32_e32 v74, v74, v1
	v_sub_f32_e32 v112, v111, v1
	v_exp_f32_e32 v111, v74
	v_sub_f32_e32 v74, v75, v1
	v_exp_f32_e32 v113, v74
	v_sub_f32_e32 v74, v76, v1
	v_exp_f32_e32 v115, v74
	v_sub_f32_e32 v74, v77, v1
	v_exp_f32_e32 v117, v74
	v_sub_f32_e32 v74, v90, v1
	v_exp_f32_e32 v119, v74
	v_sub_f32_e32 v74, v91, v1
	v_exp_f32_e32 v91, v74
	v_sub_f32_e32 v74, v92, v1
	v_exp_f32_e32 v121, v74
	v_sub_f32_e32 v74, v93, v1
	v_exp_f32_e32 v93, v74
	v_sub_f32_e32 v74, v78, v1
	v_exp_f32_e32 v123, v74
	v_sub_f32_e32 v74, v79, v1
	v_exp_f32_e32 v125, v74
	v_sub_f32_e32 v74, v80, v1
	v_exp_f32_e32 v127, v74
	v_sub_f32_e32 v74, v81, v1
	v_exp_f32_e32 v129, v74
	v_sub_f32_e32 v74, v94, v1
	v_max_f32_e32 v90, v84, v85
	v_max_f32_e32 v92, v88, v89
	v_max3_f32 v90, v82, v83, v90
	v_max3_f32 v92, v86, v87, v92
	v_exp_f32_e32 v131, v74
	v_sub_f32_e32 v74, v95, v1
	v_max3_f32 v90, v90, s41, v92
	v_exp_f32_e32 v95, v74
	v_sub_f32_e32 v74, v96, v1
	v_max_f32_e32 v92, v68, v69
	v_max_f32_e32 v94, v72, v73
	v_max3_f32 v92, v66, v67, v92
	v_max3_f32 v94, v70, v71, v94
	v_max3_f32 v90, v90, v92, v94
	ds_bpermute_b32 v92, v135, v90
	v_exp_f32_e32 v134, v112
	v_exp_f32_e32 v133, v74
	v_sub_f32_e32 v74, v97, v1
	v_exp_f32_e32 v97, v74
	s_waitcnt lgkmcnt(0)
	v_max_f32_e32 v90, v90, v92
	ds_bpermute_b32 v92, v101, v90
	v_pk_mul_f32 v[80:81], v[52:53], v[134:135] op_sel_hi:[1,0]
	v_pk_mul_f32 v[78:79], v[50:51], v[134:135] op_sel_hi:[1,0]
	v_pk_mul_f32 v[76:77], v[56:57], v[134:135] op_sel_hi:[1,0]
	v_pk_mul_f32 v[74:75], v[54:55], v[134:135] op_sel_hi:[1,0]
	s_waitcnt lgkmcnt(0)
	v_max3_f32 v152, v110, v90, v92
	v_sub_f32_e32 v82, v82, v152
	v_sub_f32_e32 v153, v110, v152
	v_exp_f32_e32 v110, v82
	v_sub_f32_e32 v82, v83, v152
	v_exp_f32_e32 v112, v82
	v_sub_f32_e32 v82, v84, v152
	v_exp_f32_e32 v114, v82
	v_sub_f32_e32 v82, v85, v152
	v_sub_f32_e32 v66, v66, v152
	v_exp_f32_e32 v116, v82
	v_sub_f32_e32 v82, v86, v152
	v_exp_f32_e32 v122, v66
	v_sub_f32_e32 v66, v67, v152
	v_exp_f32_e32 v118, v82
	v_sub_f32_e32 v82, v87, v152
	v_exp_f32_e32 v124, v66
	v_exp_f32_e32 v90, v82
	v_sub_f32_e32 v82, v88, v152
	v_pk_add_f32 v[66:67], v[112:113], v[110:111]
	v_exp_f32_e32 v120, v82
	v_sub_f32_e32 v82, v89, v152
	v_pk_add_f32 v[66:67], v[114:115], v[66:67]
	v_exp_f32_e32 v92, v82
	v_pk_add_f32 v[66:67], v[116:117], v[66:67]
	v_sub_f32_e32 v68, v68, v152
	v_pk_add_f32 v[66:67], v[118:119], v[66:67]
	v_exp_f32_e32 v126, v68
	v_pk_add_f32 v[66:67], v[90:91], v[66:67]
	v_sub_f32_e32 v68, v69, v152
	v_pk_add_f32 v[66:67], v[120:121], v[66:67]
	v_exp_f32_e32 v128, v68
	v_pk_add_f32 v[66:67], v[92:93], v[66:67]
	v_sub_f32_e32 v68, v70, v152
	v_pk_add_f32 v[66:67], v[122:123], v[66:67]
	v_exp_f32_e32 v130, v68
	v_sub_f32_e32 v68, v71, v152
	v_pk_add_f32 v[66:67], v[124:125], v[66:67]
	v_exp_f32_e32 v94, v68
	v_sub_f32_e32 v68, v72, v152
	v_exp_f32_e32 v132, v68
	v_sub_f32_e32 v68, v73, v152
	v_pk_add_f32 v[66:67], v[126:127], v[66:67]
	v_exp_f32_e32 v96, v68
	v_pk_add_f32 v[66:67], v[128:129], v[66:67]
	v_exp_f32_e32 v82, v153
	v_pk_add_f32 v[66:67], v[130:131], v[66:67]
	v_mov_b32_e32 v83, v134
	v_pk_add_f32 v[66:67], v[94:95], v[66:67]
	v_pk_add_f32 v[66:67], v[132:133], v[66:67]
	v_pk_mul_f32 v[68:69], v[36:37], v[82:83] op_sel_hi:[1,0]
	v_pk_add_f32 v[66:67], v[96:97], v[66:67]
	v_pk_mul_f32 v[72:73], v[40:41], v[82:83] op_sel_hi:[1,0]
	v_pk_fma_f32 v[104:105], v[104:105], v[82:83], v[66:67]
	v_pk_mul_f32 v[66:67], v[34:35], v[82:83] op_sel_hi:[1,0]
	v_pk_mul_f32 v[70:71], v[38:39], v[82:83] op_sel_hi:[1,0]
	v_pk_mul_f32 v[44:45], v[44:45], v[82:83] op_sel_hi:[1,0]
	v_pk_mul_f32 v[42:43], v[42:43], v[82:83] op_sel_hi:[1,0]
	v_pk_mul_f32 v[36:37], v[48:49], v[82:83] op_sel_hi:[1,0]
	v_pk_mul_f32 v[34:35], v[46:47], v[82:83] op_sel_hi:[1,0]
	ds_read_b128 v[154:157], v188 offset:25088
	ds_read_b128 v[158:161], v188 offset:27136
	ds_read_b128 v[162:165], v188 offset:29184
	ds_read_b128 v[166:169], v188 offset:31232
	ds_read_b128 v[170:173], v189 offset:27136
	ds_read_b128 v[174:177], v189 offset:25088
	ds_read_b128 v[178:181], v189 offset:29184
	ds_read_b128 v[182:185], v189 offset:31232
	v_cvt_pk_bf16_f32 v54, v111, v113
	v_cvt_pk_bf16_f32 v55, v115, v117
	v_cvt_pk_bf16_f32 v56, v119, v91
	v_cvt_pk_bf16_f32 v57, v121, v93
	v_cvt_pk_bf16_f32 v38, v110, v112
	v_cvt_pk_bf16_f32 v39, v114, v116
	v_cvt_pk_bf16_f32 v40, v118, v90
	v_cvt_pk_bf16_f32 v41, v120, v92
	v_pk_mul_f32 v[60:61], v[60:61], v[134:135] op_sel_hi:[1,0]
	s_waitcnt lgkmcnt(7)
	v_mfma_f32_16x16x32_bf16 v[78:81], v[154:157], v[54:57], v[78:81]
	v_mul_f32_e64 v58, v58, v134
	v_mul_f32_e64 v59, v59, v134
	v_pk_mul_f32 v[52:53], v[64:65], v[134:135] op_sel_hi:[1,0]
	v_pk_mul_f32 v[50:51], v[62:63], v[134:135] op_sel_hi:[1,0]
	v_mfma_f32_16x16x32_bf16 v[66:69], v[154:157], v[38:41], v[66:69]
	v_cvt_pk_bf16_f32 v62, v123, v125
	s_waitcnt lgkmcnt(6)
	v_mfma_f32_16x16x32_bf16 v[74:77], v[158:161], v[54:57], v[74:77]
	v_cvt_pk_bf16_f32 v63, v127, v129
	v_cvt_pk_bf16_f32 v64, v131, v95
	v_cvt_pk_bf16_f32 v65, v133, v97
	v_mfma_f32_16x16x32_bf16 v[70:73], v[158:161], v[38:41], v[70:73]
	v_cvt_pk_bf16_f32 v46, v122, v124
	v_cvt_pk_bf16_f32 v47, v126, v128
	s_waitcnt lgkmcnt(5)
	v_mfma_f32_16x16x32_bf16 v[58:61], v[162:165], v[54:57], v[58:61]
	v_cvt_pk_bf16_f32 v48, v130, v94
	v_cvt_pk_bf16_f32 v49, v132, v96
	v_mov_b32_e32 v110, v152
	v_mfma_f32_16x16x32_bf16 v[42:45], v[162:165], v[38:41], v[42:45]
	v_mov_b32_e32 v111, v1
	s_waitcnt lgkmcnt(4)
	v_mfma_f32_16x16x32_bf16 v[86:89], v[166:169], v[54:57], v[50:53]
	v_mfma_f32_16x16x32_bf16 v[82:85], v[166:169], v[38:41], v[34:37]
	s_waitcnt lgkmcnt(2)
	v_mfma_f32_16x16x32_bf16 v[50:53], v[174:177], v[62:65], v[78:81]
	v_mfma_f32_16x16x32_bf16 v[34:37], v[174:177], v[46:49], v[66:69]
	s_waitcnt lgkmcnt(1)
	v_mfma_f32_16x16x32_bf16 v[58:61], v[178:181], v[62:65], v[58:61]
	v_mfma_f32_16x16x32_bf16 v[42:45], v[178:181], v[46:49], v[42:45]
	v_mfma_f32_16x16x32_bf16 v[54:57], v[170:173], v[62:65], v[74:77]
	v_mfma_f32_16x16x32_bf16 v[38:41], v[170:173], v[46:49], v[70:73]
	s_waitcnt lgkmcnt(0)
	v_mfma_f32_16x16x32_bf16 v[62:65], v[182:185], v[62:65], v[86:89]
	v_mfma_f32_16x16x32_bf16 v[46:49], v[182:185], v[46:49], v[82:85]

.LBB0_220:
	s_or_b64 exec, exec, s[82:83]
	v_max_f32_e32 v1, v68, v69
	v_max_f32_e32 v112, v92, v93
	v_max3_f32 v1, v66, v67, v1
	v_max3_f32 v112, v90, v91, v112
	v_max3_f32 v1, v1, s41, v112
	v_max_f32_e32 v112, v84, v85
	v_max_f32_e32 v113, v96, v97
	v_max3_f32 v112, v82, v83, v112
	v_max3_f32 v113, v94, v95, v113
	v_max3_f32 v1, v1, v112, v113
	ds_bpermute_b32 v112, v135, v1
	s_waitcnt lgkmcnt(0)
	v_max_f32_e32 v1, v1, v112
	ds_bpermute_b32 v112, v101, v1
	s_waitcnt lgkmcnt(0)
	v_max3_f32 v1, v111, v1, v112
	v_sub_f32_e32 v66, v66, v1
	v_sub_f32_e32 v112, v111, v1
	v_exp_f32_e32 v111, v66
	v_sub_f32_e32 v66, v67, v1
	v_exp_f32_e32 v113, v66
	v_sub_f32_e32 v66, v68, v1
	v_exp_f32_e32 v115, v66
	v_sub_f32_e32 v66, v69, v1
	v_exp_f32_e32 v117, v66
	v_sub_f32_e32 v66, v90, v1
	v_exp_f32_e32 v119, v66
	v_sub_f32_e32 v66, v91, v1
	v_exp_f32_e32 v91, v66
	v_sub_f32_e32 v66, v92, v1
	v_exp_f32_e32 v121, v66
	v_sub_f32_e32 v66, v93, v1
	v_exp_f32_e32 v93, v66
	v_sub_f32_e32 v66, v82, v1
	v_exp_f32_e32 v123, v66
	v_sub_f32_e32 v66, v83, v1
	v_exp_f32_e32 v125, v66
	v_sub_f32_e32 v66, v84, v1
	v_exp_f32_e32 v127, v66
	v_sub_f32_e32 v66, v85, v1
	v_exp_f32_e32 v129, v66
	v_sub_f32_e32 v66, v94, v1
	v_max_f32_e32 v90, v88, v89
	v_max_f32_e32 v92, v76, v77
	v_max3_f32 v90, v86, v87, v90
	v_max3_f32 v92, v74, v75, v92
	v_exp_f32_e32 v131, v66
	v_sub_f32_e32 v66, v95, v1
	v_max3_f32 v90, v90, s41, v92
	v_exp_f32_e32 v95, v66
	v_sub_f32_e32 v66, v96, v1
	v_max_f32_e32 v92, v72, v73
	v_max_f32_e32 v94, v80, v81
	v_max3_f32 v92, v70, v71, v92
	v_max3_f32 v94, v78, v79, v94
	v_max3_f32 v90, v90, v92, v94
	ds_bpermute_b32 v92, v135, v90
	v_exp_f32_e32 v152, v112
	v_exp_f32_e32 v133, v66
	v_sub_f32_e32 v66, v97, v1
	v_exp_f32_e32 v97, v66
	s_waitcnt lgkmcnt(0)
	v_max_f32_e32 v90, v90, v92
	ds_bpermute_b32 v92, v101, v90
	v_pk_mul_f32 v[84:85], v[52:53], v[152:153] op_sel_hi:[1,0]
	v_pk_mul_f32 v[82:83], v[50:51], v[152:153] op_sel_hi:[1,0]
	v_pk_mul_f32 v[68:69], v[56:57], v[152:153] op_sel_hi:[1,0]
	v_pk_mul_f32 v[66:67], v[54:55], v[152:153] op_sel_hi:[1,0]
	s_waitcnt lgkmcnt(0)
	v_max3_f32 v134, v110, v90, v92
	v_sub_f32_e32 v86, v86, v134
	v_pk_mul_f32 v[60:61], v[60:61], v[152:153] op_sel_hi:[1,0]
	v_pk_mul_f32 v[58:59], v[58:59], v[152:153] op_sel_hi:[1,0]
	v_pk_mul_f32 v[52:53], v[64:65], v[152:153] op_sel_hi:[1,0]
	v_pk_mul_f32 v[50:51], v[62:63], v[152:153] op_sel_hi:[1,0]
	v_sub_f32_e32 v153, v110, v134
	v_exp_f32_e32 v110, v86
	v_sub_f32_e32 v86, v87, v134
	v_exp_f32_e32 v112, v86
	v_sub_f32_e32 v86, v88, v134
	v_sub_f32_e32 v74, v74, v134
	v_exp_f32_e32 v114, v86
	v_sub_f32_e32 v86, v89, v134
	v_exp_f32_e32 v118, v74
	v_sub_f32_e32 v74, v75, v134
	v_exp_f32_e32 v116, v86
	v_exp_f32_e32 v90, v74
	v_sub_f32_e32 v74, v76, v134
	v_sub_f32_e32 v70, v70, v134
	v_exp_f32_e32 v120, v74
	v_exp_f32_e32 v122, v70
	v_sub_f32_e32 v70, v71, v134
	v_pk_add_f32 v[74:75], v[112:113], v[110:111]
	v_exp_f32_e32 v124, v70
	v_sub_f32_e32 v70, v72, v134
	v_pk_add_f32 v[74:75], v[114:115], v[74:75]
	v_sub_f32_e32 v76, v77, v134
	v_exp_f32_e32 v126, v70
	v_sub_f32_e32 v70, v73, v134
	v_pk_add_f32 v[74:75], v[116:117], v[74:75]
	v_exp_f32_e32 v92, v76
	v_exp_f32_e32 v128, v70
	v_sub_f32_e32 v70, v78, v134
	v_pk_add_f32 v[74:75], v[118:119], v[74:75]
	v_exp_f32_e32 v130, v70
	v_sub_f32_e32 v70, v79, v134
	v_pk_add_f32 v[74:75], v[90:91], v[74:75]
	v_exp_f32_e32 v94, v70
	v_sub_f32_e32 v70, v80, v134
	v_pk_add_f32 v[74:75], v[120:121], v[74:75]
	v_exp_f32_e32 v132, v70
	v_sub_f32_e32 v70, v81, v134
	v_exp_f32_e32 v96, v70
	v_pk_add_f32 v[70:71], v[92:93], v[74:75]
	v_exp_f32_e32 v78, v153
	v_pk_add_f32 v[70:71], v[122:123], v[70:71]
	v_mov_b32_e32 v79, v152
	v_pk_add_f32 v[70:71], v[124:125], v[70:71]
	v_pk_add_f32 v[70:71], v[126:127], v[70:71]
	v_pk_mul_f32 v[76:77], v[36:37], v[78:79] op_sel_hi:[1,0]
	v_pk_add_f32 v[70:71], v[128:129], v[70:71]
	v_pk_mul_f32 v[74:75], v[34:35], v[78:79] op_sel_hi:[1,0]
	v_pk_add_f32 v[70:71], v[130:131], v[70:71]
	v_pk_mul_f32 v[72:73], v[40:41], v[78:79] op_sel_hi:[1,0]
	v_pk_add_f32 v[70:71], v[94:95], v[70:71]
	v_pk_mul_f32 v[44:45], v[44:45], v[78:79] op_sel_hi:[1,0]
	v_pk_add_f32 v[70:71], v[132:133], v[70:71]
	v_pk_mul_f32 v[42:43], v[42:43], v[78:79] op_sel_hi:[1,0]
	v_pk_add_f32 v[70:71], v[96:97], v[70:71]
	v_pk_mul_f32 v[36:37], v[48:49], v[78:79] op_sel_hi:[1,0]
	v_pk_fma_f32 v[104:105], v[104:105], v[78:79], v[70:71]
	v_pk_mul_f32 v[70:71], v[38:39], v[78:79] op_sel_hi:[1,0]
	v_pk_mul_f32 v[34:35], v[46:47], v[78:79] op_sel_hi:[1,0]
	ds_read_b128 v[154:157], v188 offset:33280
	ds_read_b128 v[158:161], v188 offset:35328
	ds_read_b128 v[162:165], v188 offset:37376
	ds_read_b128 v[166:169], v188 offset:39424
	ds_read_b128 v[170:173], v189 offset:35328
	ds_read_b128 v[174:177], v189 offset:33280
	ds_read_b128 v[178:181], v189 offset:37376
	ds_read_b128 v[182:185], v189 offset:39424
	v_cvt_pk_bf16_f32 v54, v111, v113
	v_cvt_pk_bf16_f32 v55, v115, v117
	v_cvt_pk_bf16_f32 v56, v119, v91
	v_cvt_pk_bf16_f32 v57, v121, v93
	v_cvt_pk_bf16_f32 v38, v110, v112
	v_cvt_pk_bf16_f32 v39, v114, v116
	v_cvt_pk_bf16_f32 v40, v118, v90
	v_cvt_pk_bf16_f32 v41, v120, v92
	s_waitcnt lgkmcnt(7)
	v_mfma_f32_16x16x32_bf16 v[82:85], v[154:157], v[54:57], v[82:85]
	v_cvt_pk_bf16_f32 v62, v123, v125
	v_cvt_pk_bf16_f32 v63, v127, v129
	v_cvt_pk_bf16_f32 v64, v131, v95
	v_mfma_f32_16x16x32_bf16 v[74:77], v[154:157], v[38:41], v[74:77]
	v_cvt_pk_bf16_f32 v65, v133, v97
	v_cvt_pk_bf16_f32 v46, v122, v124
	s_waitcnt lgkmcnt(6)
	v_mfma_f32_16x16x32_bf16 v[66:69], v[158:161], v[54:57], v[66:69]
	v_cvt_pk_bf16_f32 v47, v126, v128
	v_cvt_pk_bf16_f32 v48, v130, v94
	v_cvt_pk_bf16_f32 v49, v132, v96
	v_mfma_f32_16x16x32_bf16 v[70:73], v[158:161], v[38:41], v[70:73]
	v_mov_b32_e32 v110, v134
	v_mov_b32_e32 v111, v1
	s_waitcnt lgkmcnt(5)
	v_mfma_f32_16x16x32_bf16 v[58:61], v[162:165], v[54:57], v[58:61]
	v_mfma_f32_16x16x32_bf16 v[42:45], v[162:165], v[38:41], v[42:45]
	s_waitcnt lgkmcnt(4)
	v_mfma_f32_16x16x32_bf16 v[86:89], v[166:169], v[54:57], v[50:53]
	v_mfma_f32_16x16x32_bf16 v[78:81], v[166:169], v[38:41], v[34:37]
	s_waitcnt lgkmcnt(3)
	v_mfma_f32_16x16x32_bf16 v[54:57], v[170:173], v[62:65], v[66:69]
	s_waitcnt lgkmcnt(1)
	v_mfma_f32_16x16x32_bf16 v[58:61], v[178:181], v[62:65], v[58:61]
	v_mfma_f32_16x16x32_bf16 v[42:45], v[178:181], v[46:49], v[42:45]
	v_mfma_f32_16x16x32_bf16 v[50:53], v[174:177], v[62:65], v[82:85]
	v_mfma_f32_16x16x32_bf16 v[34:37], v[174:177], v[46:49], v[74:77]
	v_mfma_f32_16x16x32_bf16 v[38:41], v[170:173], v[46:49], v[70:73]
	s_waitcnt lgkmcnt(0)
	v_mfma_f32_16x16x32_bf16 v[62:65], v[182:185], v[62:65], v[86:89]
	v_mfma_f32_16x16x32_bf16 v[46:49], v[182:185], v[46:49], v[78:81]
